# k6 + loop-edge rotation (diff and MLA attention loops): loop-back barrier becomes the loop head, parity/LDS-base setup and exit test moved in front of it, exit path has its own barrier copy
# speedup vs baseline: 1.0132x; 1.0122x over previous
; template <int DK, int MODE, bool OUTF32> ...
;     ...
;     const int tid = opaque_tid(), wave = tid >> 6, lane = tid & 63, c = lane & 31, hi = lane >> 5;
;     const int rg = wave >> 1, kh = wave & 1;
;     const int qw0 = q0 + 32 * rg, qrow = qw0 + c, cw = qw0 >> 6;
;     int t_lo = 0;
;     if (MODE == 1) { t_lo = (q0 >> 6) - 8; if (t_lo < 0) t_lo = 0; }
;     const int t_hi = ((q0 + 127) >> 6) + 1;
;     bf16x8 qf[NKS];
; #pragma unroll
;     for (int s = 0; s < NKS; ++s) qf[s] = *(const bf16x8*)(Qh + (size_t)qrow * DK + 16 * s + 8 * hi);
;     float cq = 0.f;
;     if (MODE == 0) cq = cumh[qrow];
; #pragma unroll
;     for (int s = 0; s < NKS; ++s) asm volatile("" : "+v"(qf[s]));
;     asm volatile("" : "+v"(cq));
;     if (MODE == 1) { for (int i = tid; i < 257; i += NTHR) ((float*)(a_lds + OFF_RB))[i] = relb[i] * LOG2E; }
;     float cso = 0.f;
;     const float* offs = (const float*)(a_lds + OFF_RB);
;     if (MODE == 0) {
;         if (wave == 0) {
;             const float v0 = relb[lane], v1 = relb[64 + lane];
;             float s0 = v0, s1 = v1;
; #pragma unroll
;             for (int d_ = 1; d_ < 64; d_ <<= 1) {
;                 const float t0 = __int_as_float(__builtin_amdgcn_ds_bpermute((lane - d_) * 4, __float_as_int(s0)));
; __device__ __forceinline__ void attn_odd_phase(const bf16_t* __restrict__ att, bf16_t* __restrict__ Ob, float* __restrict__ A12, unsigned* ctr) {
;     ...
;         const int j = 31 - item / 48, r = item % 48;
;         if (r < 16) {
;             const int bh = r, b = bh >> 3, h = bh & 7;
;             attn_item<192, 2, false>(att + (size_t)bh * S * 192, att + MHSZ + (size_t)bh * S * 192, att + 2 * MHSZ + (size_t)bh * 128 * S,
;                                      Ob + (size_t)b * S * D + h * 128, D, j * 128, nullptr, nullptr, SC192);
;         } else {
;             const int v = r - 16, b = v >> 4, vh2 = v & 15, vh = vh2 >> 1, half = vh2 & 1, hd = vh >> 1, comp = vh & 1;
;             attn_item<128, 2, true>(att + 2 * MHSZ + EHSZ + (size_t)(b * 8 + vh) * S * 128, att + 2 * MHSZ + 2 * EHSZ + (size_t)(b * 8 + vh) * S * 128,
;                                     att + 2 * MHSZ + 3 * EHSZ + ((size_t)(b * 4 + hd) * 256 + half * 128) * S,
;                                     A12 + (size_t)b * S * D + hd * 512 + comp * 256 + half * 128, D, j * 128, nullptr, nullptr, SC128);
.LBB0_939:
	s_mov_b32 s12, 0xd5555555
	v_mul_hi_i32 v2, v1, s12
	v_lshrrev_b32_e32 v4, 31, v2
	v_ashrrev_i32_e32 v2, 3, v2
	s_mov_b32 s12, 0x2aaaaaab
	v_add3_u32 v2, v2, v4, 31
	v_mul_hi_i32 v4, v1, s12
	v_lshrrev_b32_e32 v5, 31, v4
	v_lshrrev_b32_e32 v4, 3, v4
	v_add_u32_e32 v4, v4, v5
	v_mul_lo_u32 v4, v4, 48
	v_sub_u32_e32 v156, v1, v4
	v_lshlrev_b32_e32 v4, 7, v2
	v_cmp_lt_i32_e32 vcc, 15, v156
	v_lshrrev_b32_e32 v1, 6, v4
	s_and_saveexec_b64 s[12:13], vcc
	s_xor_b64 s[46:47], exec, s[12:13]
	s_cbranch_execz .LBB0_955
	v_add_u32_e32 v2, -16, v156
	v_lshrrev_b32_e32 v2, 4, v2
	v_bfe_u32 v5, v156, 1, 3
	v_mov_b32_e32 v120, v0
	v_lshl_or_b32 v6, v2, 3, v5
	v_mov_b32_e32 v7, v3
	v_ashrrev_i32_e32 v5, 2, v120
	v_and_b32_e32 v5, 0xffffffe0, v5
	v_and_b32_e32 v121, 31, v120
	v_add_u32_e32 v123, v5, v4
	v_or_b32_e32 v166, v123, v121
	v_lshlrev_b64 v[6:7], 20, v[6:7]
	v_ashrrev_i32_e32 v167, 31, v166
	v_lshl_add_u64 v[8:9], s[78:79], 0, v[6:7]
	v_bfe_u32 v122, v120, 5, 1
	v_lshlrev_b64 v[4:5], 8, v[166:167]
	v_lshl_add_u64 v[4:5], v[8:9], 0, v[4:5]
	v_lshlrev_b32_e32 v164, 4, v122
	v_mov_b32_e32 v165, v3
	v_lshl_add_u64 v[4:5], v[4:5], 0, v[164:165]
	global_load_dwordx4 v[112:115], v[4:5], off
	global_load_dwordx4 v[108:111], v[4:5], off offset:32
	global_load_dwordx4 v[104:107], v[4:5], off offset:64
	global_load_dwordx4 v[100:103], v[4:5], off offset:96
	global_load_dwordx4 v[96:99], v[4:5], off offset:128
	global_load_dwordx4 v[92:95], v[4:5], off offset:160
	global_load_dwordx4 v[88:91], v[4:5], off offset:192
	global_load_dwordx4 v[84:87], v[4:5], off offset:224
	v_lshrrev_b32_e32 v165, 1, v156
	v_lshlrev_b32_e32 v4, 7, v156
	v_bfe_u32 v169, v165, 1, 2
	v_mov_b32_e32 v5, v3
	v_and_b32_e32 v168, 0x80, v4
	v_lshl_or_b32 v4, v2, 2, v169
	v_ashrrev_i32_e32 v10, 31, v120
	v_add_u32_e32 v11, 0x200, v120
	v_lshlrev_b64 v[4:5], 21, v[4:5]
	v_lshrrev_b32_e32 v10, 28, v10
	v_ashrrev_i32_e32 v13, 31, v11
	v_mov_b32_e32 v9, v3
	v_lshlrev_b32_e32 v8, 13, v168
	v_lshl_add_u64 v[70:71], s[52:53], 0, v[6:7]
	v_lshl_add_u64 v[4:5], s[54:55], 0, v[4:5]
	v_add_u32_e32 v6, v120, v10
	v_lshrrev_b32_e32 v7, 28, v13
	v_ashrrev_i32_e32 v68, 3, v120
	v_lshl_add_u64 v[74:75], v[4:5], 0, v[8:9]
	v_and_b32_e32 v4, -16, v6
	v_add_u32_e32 v5, v11, v7
	v_ashrrev_i32_e32 v69, 31, v68
	v_ashrrev_i32_e32 v76, 4, v6
	v_sub_u32_e32 v124, v120, v4
	v_and_b32_e32 v6, -16, v5
	v_lshlrev_b32_e32 v12, 4, v120
	v_lshlrev_b64 v[72:73], 13, v[68:69]
	v_ashrrev_i32_e32 v78, 4, v5
	v_ashrrev_i32_e32 v77, 31, v76
	v_sub_u32_e32 v125, v11, v6
	v_lshlrev_b32_e32 v6, 3, v124
	v_mov_b32_e32 v171, v3
	v_and_b32_e32 v170, 0x70, v12
	v_lshl_add_u64 v[4:5], v[74:75], 0, v[72:73]
	v_lshlrev_b64 v[80:81], 8, v[76:77]
	v_ashrrev_i32_e32 v79, 31, v78
	v_ashrrev_i32_e32 v7, 31, v6
	v_lshlrev_b32_e32 v10, 3, v125
	v_lshl_add_u64 v[4:5], v[4:5], 0, v[170:171]
	v_lshl_add_u64 v[8:9], v[70:71], 0, v[80:81]
	v_lshlrev_b64 v[82:83], 8, v[78:79]
	s_mov_b32 s12, 0x80000
	v_lshlrev_b64 v[116:117], 1, v[6:7]
	v_ashrrev_i32_e32 v11, 31, v10
	v_mov_b32_e32 v14, v3
	v_add_co_u32_e32 v12, vcc, s12, v4
	v_lshl_add_u64 v[6:7], v[70:71], 0, v[82:83]
	v_lshl_add_u64 v[8:9], v[8:9], 0, v[116:117]
	v_lshlrev_b64 v[118:119], 1, v[10:11]
	v_addc_co_u32_e32 v13, vcc, 0, v5, vcc
	v_lshl_add_u64 v[6:7], v[6:7], 0, v[118:119]
	v_ashrrev_i32_e32 v171, 6, v120
	s_movk_i32 s13, 0x88
	v_and_b32_e32 v180, 1, v171
	v_mul_lo_u32 v185, v68, s13
	v_mad_u32_u24 v68, v121, s13, 0
	s_movk_i32 s13, 0x110
	v_and_b32_e32 v178, 63, v120
	v_lshlrev_b32_e32 v69, 3, v122
	global_load_dwordx4 v[52:55], v[8:9], off
	global_load_dwordx4 v[56:59], v[6:7], off
	global_load_dwordx4 v[60:63], v[4:5], off
	global_load_dwordx4 v[64:67], v[12:13], off
	v_lshlrev_b32_e32 v120, 6, v180
	v_mul_lo_u32 v188, v76, s13
	v_or_b32_e32 v72, v72, v170
	v_lshlrev_b32_e32 v189, 4, v124
	v_mov_b32_e32 v18, v3
	v_mov_b32_e32 v19, v3
	v_add3_u32 v77, 0, v185, v170
	v_lshl_or_b32 v79, v180, 5, v121
	v_add3_u32 v184, v68, v69, v120
	v_lshl_add_u64 v[68:69], v[70:71], 0, s[10:11]
	v_mul_lo_u32 v190, v78, s13
	v_lshl_add_u64 v[70:71], v[74:75], 0, v[72:73]
	v_add3_u32 v74, 0, v188, v189
	v_lshlrev_b32_e32 v191, 4, v125
	s_mov_b64 s[10:11], 0x80080
	v_mov_b32_e32 v4, v3
	v_mov_b32_e32 v5, v3
	v_mov_b32_e32 v6, v3
	v_mov_b32_e32 v7, v3
	v_mov_b32_e32 v8, v3
	v_mov_b32_e32 v9, v3
	v_mov_b32_e32 v10, v3
	v_mov_b32_e32 v11, v3
	v_mov_b32_e32 v12, v3
	v_mov_b32_e32 v13, v3
	v_mov_b32_e32 v14, v3
	v_mov_b32_e32 v15, v3
	v_mov_b32_e32 v16, v3
	v_mov_b32_e32 v17, v3
	v_mov_b64_e32 v[50:51], v[18:19]
	v_mov_b64_e32 v[34:35], v[18:19]
	v_add_u32_e32 v121, 0xc800, v77
	v_add_u32_e32 v77, 0xea00, v77
	v_mul_u32_u24_e32 v79, 0x110, v79
	v_lshl_add_u64 v[172:173], v[70:71], 0, s[10:11]
	v_add3_u32 v75, 0, v190, v191
	v_lshl_add_u64 v[70:71], v[80:81], 0, v[116:117]
	v_lshl_add_u64 v[72:73], v[82:83], 0, v[118:119]
	s_mov_b32 s12, 0
	v_or_b32_e32 v182, 1, v1
	v_mov_b32_e32 v179, 0
	v_mov_b32_e32 v181, 0xf149f2ca
	s_mov_b64 s[42:43], 0
	v_mov_b64_e32 v[48:49], v[16:17]
	v_mov_b64_e32 v[46:47], v[14:15]
	v_mov_b64_e32 v[44:45], v[12:13]
	v_mov_b64_e32 v[42:43], v[10:11]
	v_mov_b64_e32 v[40:41], v[8:9]
	v_mov_b64_e32 v[38:39], v[6:7]
	v_mov_b64_e32 v[36:37], v[4:5]
	v_mov_b64_e32 v[32:33], v[16:17]
	v_mov_b64_e32 v[30:31], v[14:15]
	v_mov_b64_e32 v[28:29], v[12:13]
	v_mov_b64_e32 v[26:27], v[10:11]
	v_mov_b64_e32 v[24:25], v[8:9]
	v_mov_b64_e32 v[22:23], v[6:7]
	v_mov_b64_e32 v[20:21], v[4:5]
	v_add_u32_e32 v186, 0x2200, v185
	v_ashrrev_i32_e32 v187, 6, v123
	v_add3_u32 v183, 0, v79, v164
	v_lshl_add_u64 v[174:175], v[68:69], 0, v[70:71]
	v_lshl_add_u64 v[176:177], v[68:69], 0, v[72:73]
	s_waitcnt vmcnt(3)
	ds_write_b128 v74, v[52:55]
	s_waitcnt vmcnt(2)
	ds_write_b128 v75, v[56:59]
	s_waitcnt vmcnt(1)
	ds_write2_b64 v121, v[60:61], v[62:63] offset1:1
	s_waitcnt vmcnt(0)
	ds_write2_b64 v77, v[64:65], v[66:67] offset1:1
	v_mov_b64_e32 v[66:67], v[18:19]
	v_mov_b64_e32 v[64:65], v[16:17]
	v_mov_b64_e32 v[62:63], v[14:15]
	v_mov_b64_e32 v[60:61], v[12:13]
	v_mov_b64_e32 v[58:59], v[10:11]
	v_mov_b64_e32 v[56:57], v[8:9]
	v_mov_b64_e32 v[54:55], v[6:7]
	v_mov_b64_e32 v[52:53], v[4:5]
	s_and_b32 s13, s12, 1
	s_mul_i32 s14, s13, 0x4400
	v_add_u32_e32 v242, s14, v183
	v_add_u32_e32 v196, s14, v184
	s_waitcnt lgkmcnt(0)
	s_branch .Ldq_bar

; template <int DK, int MODE, bool OUTF32> ...
;     ...
;     for (int t = t_lo; t < t_hi; ++t) {
;         const int cur = (t - t_lo) & 1;
;         if (t + 1 < t_hi) A_ISSUE(t + 1);
;         bool act;
;         if (MODE == 0) act = (64 * t + 32 * kh) <= (qw0 + 31);
;         else if (MODE == 1) act = (t <= cw) && (t >= cw - 8);
;         else act = (t <= cw);
;         if (act) {
;             f32x16 p;
; #pragma unroll
;             for (int r = 0; r < 16; ++r) p[r] = 0.f;
;             const unsigned char* kb = a_lds + cur * KBUF + (32 * kh + c) * KP + hi * 16;
;             constexpr bool HOISTK = true;
;             bf16x8 kf[NKS];
;             if (HOISTK) {
; #pragma unroll
;                 for (int s = 0; s < NKS; ++s) kf[s] = *(const bf16x8*)(kb + s * 32);
;             }
;             const unsigned char* vb = a_lds + OFF_V + cur * VBUF + c * VP + (32 * kh + 4 * hi) * 2;
;             bf16x8 vf[8];
;     ...
;             constexpr bool HOISTV = (DK == 128) && (MODE == 2 || MODE == 1);
;             if (HOISTV) A_VREADS(0, 3);
;             if (HOISTK) __builtin_amdgcn_sched_barrier(0);
; #pragma unroll
;             for (int s = 0; s < NKS; ++s) p = __builtin_amdgcn_mfma_f32_32x32x16_bf16(HOISTK ? kf[s] : *(const bf16x8*)(kb + s * 32), qf[s], p, 0, 0, 0);
;             if (HOISTV) { A_VREADS(3, 4); __builtin_amdgcn_sched_barrier(0); }
;             if (MODE == 0) {
;                 const float* ckp = (const float*)(a_lds + OFF_CK + cur * 256) + 32 * kh + 4 * hi;
; #pragma unroll
;                 for (int g = 0; g < 4; ++g) {
;                     const float4 ck = *(const float4*)(ckp + 8 * g);
;                     p[4 * g + 0] = fmaf(p[4 * g + 0], sc2, cq - ck.x); p[4 * g + 1] = fmaf(p[4 * g + 1], sc2, cq - ck.y);
;                     p[4 * g + 2] = fmaf(p[4 * g + 2], sc2, cq - ck.z); p[4 * g + 3] = fmaf(p[4 * g + 3], sc2, cq - ck.w);
;                 }
;                 if (64 * t + 32 * kh + 31 > qw0) {
;                     const int kbase = 64 * t + 32 * kh + 4 * hi;
; #pragma unroll
;                     for (int r = 0; r < 16; ++r) if (kbase + (r & 3) + 8 * (r >> 2) > qrow) p[r] = NEGINF;
;                 }
;             } else if (MODE == 1) {
;                 const float* rb = (const float*)(a_lds + OFF_RB);
;                 if (t <= cw - 3) {
;                     const float bb = rb[256];
; #pragma unroll
.LBB0_942:
	s_or_b64 exec, exec, s[50:51]
	s_xor_b32 s13, s13, 1
	s_mulk_i32 s13, 0x4400
	s_add_i32 s13, s13, 0
	v_add3_u32 v68, s13, v188, v189
	s_waitcnt vmcnt(3)
	ds_write_b128 v68, v[120:123]
	v_add3_u32 v68, s13, v190, v191
	s_waitcnt vmcnt(2)
	ds_write_b128 v68, v[116:119]
	v_add_u32_e32 v68, s13, v185
	s_mov_b32 s14, 0xc800
	v_add3_u32 v68, v68, v170, s14
	s_add_i32 s12, s12, 1
	s_waitcnt vmcnt(1)
	ds_write2_b64 v68, v[128:129], v[130:131] offset1:1
	v_add_u32_e32 v68, s13, v186
	v_add3_u32 v68, v68, v170, s14
	s_mov_b64 s[14:15], 0x4000
	v_cmp_eq_u32_e32 vcc, s12, v182
	v_lshl_add_u64 v[172:173], v[172:173], 0, s[88:89]
	v_lshl_add_u64 v[176:177], v[176:177], 0, s[14:15]
	s_or_b64 s[42:43], vcc, s[42:43]
	s_mov_b64 s[10:11], 0x4000
	v_lshl_add_u64 v[174:175], v[174:175], 0, s[14:15]
	s_waitcnt vmcnt(0)
	ds_write2_b64 v68, v[124:125], v[126:127] offset1:1
	s_and_b32 s13, s12, 1
	s_mul_i32 s14, s13, 0x4400
	v_add_u32_e32 v242, s14, v183
	v_add_u32_e32 v196, s14, v184
	s_waitcnt lgkmcnt(0)
	s_andn2_b64 exec, exec, s[42:43]
	s_cbranch_execz .Ldq_exit
.Ldq_bar:
	s_barrier
.LBB0_943:
	v_cmp_le_i32_e32 vcc, s12, v187
	s_and_saveexec_b64 s[50:51], vcc
	s_cbranch_execz .Ldiff_inact
	ds_read_b128 v[68:71], v242
	ds_read_b128 v[156:159], v242 offset:32
	ds_read_b128 v[160:163], v242 offset:64
	ds_read_b128 v[192:195], v242 offset:96
	ds_read_b128 v[208:211], v242 offset:128
	ds_read_b128 v[212:215], v242 offset:160
	ds_read_b128 v[216:219], v242 offset:192
	ds_read_b128 v[220:223], v242 offset:224
	v_add_u32_e32 v72, 0xc800, v196
	ds_read2_b64 v[132:135], v72 offset1:2
	ds_read2_b64 v[136:139], v72 offset0:4 offset1:6
	v_add_u32_e32 v72, 0xd800, v196
	ds_read2_b64 v[140:143], v72 offset0:32 offset1:34
	ds_read2_b64 v[144:147], v72 offset0:36 offset1:38
	v_add_u32_e32 v72, 0xe800, v196
	ds_read2_b64 v[148:151], v72 offset0:64 offset1:66
	ds_read2_b64 v[152:155], v72 offset0:68 offset1:70
	v_add_co_u32_e32 v240, vcc, 0xfff80000, v172
	global_load_dwordx4 v[120:123], v[174:175], off
	global_load_dwordx4 v[116:119], v[176:177], off
	v_addc_co_u32_e32 v241, vcc, -1, v173, vcc
	global_load_dwordx4 v[128:131], v[240:241], off
	global_load_dwordx4 v[124:127], v[172:173], off
	s_waitcnt lgkmcnt(13)
	v_mfma_f32_32x32x16_bf16 v[68:83], v[68:71], v[112:115], 0
	s_waitcnt lgkmcnt(12)
	v_mfma_f32_32x32x16_bf16 v[68:83], v[156:159], v[108:111], v[68:83]
	v_add_u32_e32 v156, 0xf800, v196
	s_waitcnt lgkmcnt(11)
	v_mfma_f32_32x32x16_bf16 v[68:83], v[160:163], v[104:107], v[68:83]
	ds_read2_b64 v[160:163], v156 offset0:96 offset1:98
	ds_read2_b64 v[156:159], v156 offset0:100 offset1:102
	s_waitcnt lgkmcnt(12)
	v_mfma_f32_32x32x16_bf16 v[68:83], v[192:195], v[100:103], v[68:83]
	s_waitcnt lgkmcnt(11)
	v_mfma_f32_32x32x16_bf16 v[68:83], v[208:211], v[96:99], v[68:83]
	s_waitcnt lgkmcnt(10)
	v_mfma_f32_32x32x16_bf16 v[68:83], v[212:215], v[92:95], v[68:83]
	s_waitcnt lgkmcnt(9)
	v_mfma_f32_32x32x16_bf16 v[68:83], v[216:219], v[88:91], v[68:83]
	s_waitcnt lgkmcnt(8)
	v_mfma_f32_32x32x16_bf16 v[68:83], v[220:223], v[84:87], v[68:83]
	s_nop 11
	v_max_f32_e32 v192, v69, v69
	v_max_f32_e32 v193, v68, v68
	v_max_f32_e32 v192, v193, v192
	v_max3_f32 v192, v192, v70, v71
	v_max3_f32 v192, v192, v72, v73
	v_max3_f32 v192, v192, v74, v75
	v_max3_f32 v192, v192, v76, v77
	v_max3_f32 v192, v192, v78, v79
	v_max3_f32 v192, v192, v80, v81
	v_max3_f32 v192, v192, v82, v83
	v_mul_f32_e32 v192, 0x3e0293ee, v192
	v_mov_b32_e32 v193, v192
	s_nop 1
	v_permlane32_swap_b32_e32 v192, v193
	v_max_f32_e32 v193, v193, v193
	v_max_f32_e32 v192, v192, v192
	v_max_f32_e32 v192, v192, v193
	v_sub_f32_e32 v193, v192, v181
	s_mov_b32 s14, 0x41000000
	v_cmp_ge_f32_e32 vcc, s14, v193
	s_cmp_eq_u64 vcc, exec
	s_cbranch_scc1 .LBB0_941
	v_max_f32_e32 v192, v192, v192
	v_max_f32_e32 v193, v181, v181
	v_max_f32_e32 v193, v193, v192
	v_sub_f32_e32 v181, v181, v193
	v_exp_f32_e32 v192, v181
	v_mov_b32_e32 v181, v193
	v_pk_mul_f32 v[66:67], v[66:67], v[192:193] op_sel_hi:[1,0]
	v_pk_mul_f32 v[64:65], v[64:65], v[192:193] op_sel_hi:[1,0]
	v_pk_mul_f32 v[62:63], v[62:63], v[192:193] op_sel_hi:[1,0]
	v_pk_mul_f32 v[60:61], v[60:61], v[192:193] op_sel_hi:[1,0]
	v_pk_mul_f32 v[58:59], v[58:59], v[192:193] op_sel_hi:[1,0]
	v_pk_mul_f32 v[56:57], v[56:57], v[192:193] op_sel_hi:[1,0]
	v_pk_mul_f32 v[54:55], v[54:55], v[192:193] op_sel_hi:[1,0]
	v_pk_mul_f32 v[52:53], v[52:53], v[192:193] op_sel_hi:[1,0]
	v_pk_mul_f32 v[34:35], v[34:35], v[192:193] op_sel_hi:[1,0]
	v_pk_mul_f32 v[32:33], v[32:33], v[192:193] op_sel_hi:[1,0]
	v_pk_mul_f32 v[30:31], v[30:31], v[192:193] op_sel_hi:[1,0]
	v_pk_mul_f32 v[28:29], v[28:29], v[192:193] op_sel_hi:[1,0]
	v_pk_mul_f32 v[26:27], v[26:27], v[192:193] op_sel_hi:[1,0]
	v_pk_mul_f32 v[24:25], v[24:25], v[192:193] op_sel_hi:[1,0]
	v_pk_mul_f32 v[22:23], v[22:23], v[192:193] op_sel_hi:[1,0]
	v_pk_mul_f32 v[20:21], v[20:21], v[192:193] op_sel_hi:[1,0]
	v_pk_mul_f32 v[50:51], v[50:51], v[192:193] op_sel_hi:[1,0]
	v_pk_mul_f32 v[48:49], v[48:49], v[192:193] op_sel_hi:[1,0]
	v_pk_mul_f32 v[46:47], v[46:47], v[192:193] op_sel_hi:[1,0]
	v_pk_mul_f32 v[44:45], v[44:45], v[192:193] op_sel_hi:[1,0]
	v_pk_mul_f32 v[42:43], v[42:43], v[192:193] op_sel_hi:[1,0]
	v_pk_mul_f32 v[40:41], v[40:41], v[192:193] op_sel_hi:[1,0]
	v_pk_mul_f32 v[38:39], v[38:39], v[192:193] op_sel_hi:[1,0]
	v_pk_mul_f32 v[36:37], v[36:37], v[192:193] op_sel_hi:[1,0]
	v_pk_mul_f32 v[18:19], v[18:19], v[192:193] op_sel_hi:[1,0]
	v_pk_mul_f32 v[16:17], v[16:17], v[192:193] op_sel_hi:[1,0]
	v_pk_mul_f32 v[14:15], v[14:15], v[192:193] op_sel_hi:[1,0]
	v_pk_mul_f32 v[12:13], v[12:13], v[192:193] op_sel_hi:[1,0]
	v_pk_mul_f32 v[10:11], v[10:11], v[192:193] op_sel_hi:[1,0]
	v_pk_mul_f32 v[8:9], v[8:9], v[192:193] op_sel_hi:[1,0]
	v_pk_mul_f32 v[6:7], v[6:7], v[192:193] op_sel_hi:[1,0]
	v_pk_mul_f32 v[4:5], v[4:5], v[192:193] op_sel_hi:[1,0]
	v_mul_f32_e32 v179, v179, v192
	s_branch .LBB0_941
.Ldq_exit:
	s_barrier
	s_branch .LBB0_946

; template <int DK, int MODE, bool OUTF32> ...
;     ...
;     const int tid = opaque_tid(), wave = tid >> 6, lane = tid & 63, c = lane & 31, hi = lane >> 5;
;     const int rg = wave >> 1, kh = wave & 1;
;     const int qw0 = q0 + 32 * rg, qrow = qw0 + c, cw = qw0 >> 6;
;     int t_lo = 0;
;     if (MODE == 1) { t_lo = (q0 >> 6) - 8; if (t_lo < 0) t_lo = 0; }
;     const int t_hi = ((q0 + 127) >> 6) + 1;
;     bf16x8 qf[NKS];
; #pragma unroll
;     for (int s = 0; s < NKS; ++s) qf[s] = *(const bf16x8*)(Qh + (size_t)qrow * DK + 16 * s + 8 * hi);
;     float cq = 0.f;
;     if (MODE == 0) cq = cumh[qrow];
; #pragma unroll
;     for (int s = 0; s < NKS; ++s) asm volatile("" : "+v"(qf[s]));
;     asm volatile("" : "+v"(cq));
;     if (MODE == 1) { for (int i = tid; i < 257; i += NTHR) ((float*)(a_lds + OFF_RB))[i] = relb[i] * LOG2E; }
;     float cso = 0.f;
;     const float* offs = (const float*)(a_lds + OFF_RB);
;     if (MODE == 0) {
;         if (wave == 0) {
;             const float v0 = relb[lane], v1 = relb[64 + lane];
;             float s0 = v0, s1 = v1;
; #pragma unroll
;             for (int d_ = 1; d_ < 64; d_ <<= 1) {
;                 const float t0 = __int_as_float(__builtin_amdgcn_ds_bpermute((lane - d_) * 4, __float_as_int(s0)));
;                 const float t1 = __int_as_float(__builtin_amdgcn_ds_bpermute((lane - d_) * 4, __float_as_int(s1)));
;                 if (lane >= d_) { s0 += t0; s1 += t1; }
;             }
;             const float tot0 = __int_as_float(__builtin_amdgcn_readlane(__float_as_int(s0), 63));
;             ((float*)(a_lds + OFF_RB))[lane] = s0 - v0; ((float*)(a_lds + OFF_RB))[64 + lane] = s1 - v1 + tot0;
;         }
;         __syncthreads();
;         cq += offs[qrow >> 5];
;     }
;     u32x4 kst0, kst1, kst2 = u32x4{0u, 0u, 0u, 0u}, vst0, vst1; f32x4 cst = f32x4{0.f, 0.f, 0.f, 0.f};
; __device__ __forceinline__ void attn_odd_phase(const bf16_t* __restrict__ att, bf16_t* __restrict__ Ob, float* __restrict__ A12, unsigned* ctr) {
;     ...
;             const int bh = r, b = bh >> 3, h = bh & 7;
;             attn_item<192, 2, false>(att + (size_t)bh * S * 192, att + MHSZ + (size_t)bh * S * 192, att + 2 * MHSZ + (size_t)bh * 128 * S,
;                                      Ob + (size_t)b * S * D + h * 128, D, j * 128, nullptr, nullptr, SC192);
.LBB0_955:
	s_andn2_saveexec_b64 s[46:47], s[46:47]
	s_cbranch_execz .LBB0_971
	v_mov_b32_e32 v24, v0
	v_mul_hi_i32_i24_e32 v7, 0xc0000, v156
	v_ashrrev_i32_e32 v2, 2, v24
	v_mul_i32_i24_e32 v6, 0xc0000, v156
	v_and_b32_e32 v2, 0xffffffe0, v2
	v_lshlrev_b64 v[6:7], 1, v[6:7]
	v_and_b32_e32 v25, 31, v24
	v_add_u32_e32 v26, v2, v4
	v_lshl_add_u64 v[8:9], s[18:19], 0, v[6:7]
	v_bfe_u32 v170, v24, 5, 1
	v_or_b32_e32 v154, v26, v25
	v_mad_i64_i32 v[4:5], s[12:13], v154, s69, v[8:9]
	v_lshlrev_b32_e32 v2, 4, v170
	v_lshl_add_u64 v[4:5], v[4:5], 0, v[2:3]
	global_load_dwordx4 v[142:145], v[4:5], off
	global_load_dwordx4 v[138:141], v[4:5], off offset:32
	global_load_dwordx4 v[134:137], v[4:5], off offset:64
	global_load_dwordx4 v[130:133], v[4:5], off offset:96
	global_load_dwordx4 v[126:129], v[4:5], off offset:128
	global_load_dwordx4 v[122:125], v[4:5], off offset:160
	global_load_dwordx4 v[118:121], v[4:5], off offset:192
	global_load_dwordx4 v[114:117], v[4:5], off offset:224
	global_load_dwordx4 v[110:113], v[4:5], off offset:256
	global_load_dwordx4 v[106:109], v[4:5], off offset:288
	global_load_dwordx4 v[102:105], v[4:5], off offset:320
	global_load_dwordx4 v[98:101], v[4:5], off offset:352
	v_ashrrev_i32_e32 v157, 31, v156
	v_lshlrev_b64 v[4:5], 20, v[156:157]
	s_mov_b32 s12, 0x2aaaaaab
	v_lshl_add_u64 v[18:19], s[40:41], 0, v[4:5]
	v_mul_hi_i32 v4, v24, s12
	v_add_u32_e32 v10, 0x200, v24
	v_lshl_add_u64 v[158:159], s[56:57], 0, v[6:7]
	v_lshrrev_b32_e32 v5, 31, v4
	v_ashrrev_i32_e32 v4, 2, v4
	v_mul_hi_i32 v6, v10, s12
	v_add_u32_e32 v11, 0x400, v24
	v_add_u32_e32 v76, v4, v5
	v_lshrrev_b32_e32 v4, 31, v6
	v_ashrrev_i32_e32 v5, 2, v6
	v_ashrrev_i32_e32 v20, 3, v24
	v_mul_hi_i32 v7, v11, s12
	v_add_u32_e32 v77, v5, v4
	v_ashrrev_i32_e32 v21, 31, v20
	v_lshrrev_b32_e32 v6, 31, v7
	v_ashrrev_i32_e32 v7, 2, v7
	v_mul_lo_u32 v8, v76, 24
	v_mul_lo_u32 v12, v77, 24
	v_lshlrev_b64 v[22:23], 13, v[20:21]
	v_add_u32_e32 v78, v7, v6
	v_sub_u32_e32 v21, v24, v8
	v_sub_u32_e32 v27, v10, v12
	v_mul_lo_u32 v13, v78, 24
	v_lshlrev_b32_e32 v10, 3, v21
	v_lshlrev_b32_e32 v12, 3, v27
	v_sub_u32_e32 v28, v11, v13
	v_ashrrev_i32_e32 v11, 31, v10
	v_ashrrev_i32_e32 v13, 31, v12
	v_mad_i64_i32 v[4:5], s[12:13], v76, s69, v[158:159]
	v_mad_i64_i32 v[6:7], s[12:13], v77, s69, v[158:159]
	v_lshlrev_b32_e32 v14, 3, v28
	v_lshlrev_b64 v[70:71], 1, v[10:11]
	v_lshlrev_b64 v[72:73], 1, v[12:13]
	v_mov_b32_e32 v16, v3
	v_ashrrev_i32_e32 v15, 31, v14
	v_lshl_add_u64 v[4:5], v[4:5], 0, v[70:71]
	v_lshl_add_u64 v[6:7], v[6:7], 0, v[72:73]
	v_mad_i64_i32 v[8:9], s[12:13], v78, s69, v[158:159]
	v_lshlrev_b64 v[74:75], 1, v[14:15]
	v_lshl_add_u64 v[8:9], v[8:9], 0, v[74:75]
	v_mov_b32_e32 v161, v3
	s_mov_b32 s12, 0x80000
	v_ashrrev_i32_e32 v157, 6, v24
	s_movk_i32 s13, 0x88
	v_and_b32_e32 v172, 1, v157
	v_mul_lo_u32 v177, v20, s13
	v_mad_u32_u24 v20, v25, s13, 0
	s_movk_i32 s13, 0x190
	s_mov_b64 s[14:15], 0x80080
	v_lshl_or_b32 v25, v172, 5, v25
	v_mul_lo_u32 v180, v76, s13
	v_lshlrev_b32_e32 v183, 4, v21
	global_load_dwordx4 v[34:37], v[4:5], off
	global_load_dwordx4 v[38:41], v[6:7], off
	v_lshlrev_b32_e32 v6, 4, v24
	v_lshl_add_u64 v[4:5], v[18:19], 0, v[22:23]
	v_and_b32_e32 v160, 0x70, v6
	v_lshl_add_u64 v[4:5], v[4:5], 0, v[160:161]
	global_load_dwordx4 v[42:45], v[8:9], off
	global_load_dwordx4 v[46:49], v[4:5], off
	v_add_co_u32_e32 v4, vcc, s12, v4
	v_or_b32_e32 v22, v22, v160
	s_nop 0
	v_addc_co_u32_e32 v5, vcc, 0, v5, vcc
	global_load_dwordx4 v[66:69], v[4:5], off
	v_lshl_add_u64 v[18:19], v[18:19], 0, v[22:23]
	v_add3_u32 v29, 0, v177, v160
	v_lshl_add_u64 v[162:163], v[18:19], 0, s[14:15]
	v_mad_i64_i32 v[70:71], s[14:15], v76, s69, v[70:71]
	v_mad_i64_i32 v[74:75], s[14:15], v78, s69, v[74:75]
	v_mad_i64_i32 v[72:73], s[14:15], v77, s69, v[72:73]
	v_mov_b32_e32 v16, v3
	v_mov_b32_e32 v17, v3
	v_and_b32_e32 v161, 63, v24
	v_lshlrev_b32_e32 v24, 3, v170
	v_lshlrev_b32_e32 v30, 6, v172
	v_add_u32_e32 v79, 0xc800, v29
	v_add_u32_e32 v80, 0xea00, v29
	v_mul_u32_u24_e32 v25, 0x190, v25
	v_mul_lo_u32 v181, v77, s13
	v_mul_lo_u32 v182, v78, s13
	v_add3_u32 v81, 0, v180, v183
	v_lshlrev_b32_e32 v184, 4, v27
	v_lshlrev_b32_e32 v185, 4, v28
	s_mov_b64 s[14:15], 0x6000
	v_mov_b32_e32 v4, v3
	v_mov_b32_e32 v5, v3
	v_mov_b32_e32 v6, v3
	v_mov_b32_e32 v7, v3
	v_mov_b32_e32 v8, v3
	v_mov_b32_e32 v9, v3
	v_mov_b32_e32 v10, v3
	v_mov_b32_e32 v11, v3
	v_mov_b32_e32 v12, v3
	v_mov_b32_e32 v13, v3
	v_mov_b32_e32 v14, v3
	v_mov_b32_e32 v15, v3
	v_ashrrev_i32_e32 v179, 6, v26
	v_add3_u32 v174, v20, v24, v30
	v_add3_u32 v176, 0, v25, v2
	v_mov_b32_e32 v2, v3
	v_mov_b64_e32 v[32:33], v[16:17]
	v_mov_b64_e32 v[64:65], v[16:17]
	v_add3_u32 v82, 0, v181, v184
	v_add3_u32 v83, 0, v182, v185
	v_lshl_add_u64 v[164:165], v[70:71], 0, s[14:15]
	v_lshl_add_u64 v[166:167], v[74:75], 0, s[14:15]
	v_lshl_add_u64 v[168:169], v[72:73], 0, s[14:15]
	s_mov_b32 s12, 0
	v_or_b32_e32 v175, 1, v1
	v_mov_b32_e32 v171, 0
	v_mov_b32_e32 v173, 0xf149f2ca
	s_mov_b64 s[42:43], 0
	v_add_u32_e32 v178, 0x2200, v177
	v_ashrrev_i32_e32 v155, 31, v154
	v_mov_b64_e32 v[30:31], v[14:15]
	v_mov_b64_e32 v[28:29], v[12:13]
	v_mov_b64_e32 v[26:27], v[10:11]
	v_mov_b64_e32 v[24:25], v[8:9]
	v_mov_b64_e32 v[22:23], v[6:7]
	v_mov_b64_e32 v[20:21], v[4:5]
	s_waitcnt vmcnt(4)
	ds_write_b128 v81, v[34:37]
	s_waitcnt vmcnt(3)
	ds_write_b128 v82, v[38:41]
	s_waitcnt vmcnt(2)
	ds_write_b128 v83, v[42:45]
	s_waitcnt vmcnt(1)
	ds_write2_b64 v79, v[46:47], v[48:49] offset1:1
	s_waitcnt vmcnt(0)
	ds_write2_b64 v80, v[66:67], v[68:69] offset1:1
	v_mov_b64_e32 v[48:49], v[16:17]
	v_mov_b64_e32 v[80:81], v[16:17]
	v_mov_b64_e32 v[18:19], v[2:3]
	v_mov_b64_e32 v[62:63], v[14:15]
	v_mov_b64_e32 v[60:61], v[12:13]
	v_mov_b64_e32 v[58:59], v[10:11]
	v_mov_b64_e32 v[56:57], v[8:9]
	v_mov_b64_e32 v[54:55], v[6:7]
	v_mov_b64_e32 v[52:53], v[4:5]
	v_mov_b64_e32 v[50:51], v[2:3]
	s_mov_b64 s[16:17], 0x6000
	v_mov_b64_e32 v[46:47], v[14:15]
	v_mov_b64_e32 v[44:45], v[12:13]
	v_mov_b64_e32 v[42:43], v[10:11]
	v_mov_b64_e32 v[40:41], v[8:9]
	v_mov_b64_e32 v[38:39], v[6:7]
	v_mov_b64_e32 v[36:37], v[4:5]
	v_mov_b64_e32 v[34:35], v[2:3]
	v_mov_b64_e32 v[78:79], v[14:15]
	v_mov_b64_e32 v[76:77], v[12:13]
	v_mov_b64_e32 v[74:75], v[10:11]
	v_mov_b64_e32 v[72:73], v[8:9]
	v_mov_b64_e32 v[70:71], v[6:7]
	v_mov_b64_e32 v[68:69], v[4:5]
	v_mov_b64_e32 v[66:67], v[2:3]
	s_and_b32 s13, s12, 1
	s_mul_i32 s14, s13, 0x6400
	v_add_u32_e32 v254, s14, v176
	s_waitcnt lgkmcnt(0)
	s_branch .Lmq_bar

; template <int DK, int MODE, bool OUTF32> ...
;     ...
;     for (int t = t_lo; t < t_hi; ++t) {
;         const int cur = (t - t_lo) & 1;
;         if (t + 1 < t_hi) A_ISSUE(t + 1);
.LBB0_958:
	s_or_b64 exec, exec, s[50:51]
	s_xor_b32 s13, s13, 1
	s_mul_i32 s14, s13, 0x6400
	s_add_i32 s14, s14, 0
	v_add3_u32 v2, s14, v180, v183
	s_waitcnt vmcnt(4)
	ds_write_b128 v2, v[12:15]
	v_add3_u32 v2, s14, v181, v184
	s_lshl_b32 s13, s13, 13
	s_waitcnt vmcnt(3)
	ds_write_b128 v2, v[4:7]
	v_add3_u32 v2, s14, v182, v185
	s_sub_i32 s13, s14, s13
	s_waitcnt vmcnt(2)
	ds_write_b128 v2, v[8:11]
	v_add_u32_e32 v2, s13, v177
	s_mov_b32 s14, 0xc800
	s_add_i32 s12, s12, 1
	v_add3_u32 v2, v2, v160, s14
	s_waitcnt vmcnt(1)
	ds_write2_b64 v2, v[150:151], v[152:153] offset1:1
	v_add_u32_e32 v2, s13, v178
	v_cmp_eq_u32_e32 vcc, s12, v175
	v_add3_u32 v2, v2, v160, s14
	v_lshl_add_u64 v[162:163], v[162:163], 0, s[88:89]
	s_or_b64 s[42:43], vcc, s[42:43]
	v_lshl_add_u64 v[158:159], v[158:159], 0, s[16:17]
	s_waitcnt vmcnt(0)
	ds_write2_b64 v2, v[146:147], v[148:149] offset1:1
	s_and_b32 s13, s12, 1
	s_mul_i32 s14, s13, 0x6400
	v_add_u32_e32 v254, s14, v176
	s_waitcnt lgkmcnt(0)
	s_andn2_b64 exec, exec, s[42:43]
	s_cbranch_execz .Lmq_exit

; template <int DK, int MODE, bool OUTF32> ...
;     ...
;     for (int t = t_lo; t < t_hi; ++t) {
;         const int cur = (t - t_lo) & 1;
;         if (t + 1 < t_hi) A_ISSUE(t + 1);
;         bool act;
;         if (MODE == 0) act = (64 * t + 32 * kh) <= (qw0 + 31);
;         else if (MODE == 1) act = (t <= cw) && (t >= cw - 8);
;         else act = (t <= cw);
;         if (act) {
;             f32x16 p;
; #pragma unroll
;             for (int r = 0; r < 16; ++r) p[r] = 0.f;
;             const unsigned char* kb = a_lds + cur * KBUF + (32 * kh + c) * KP + hi * 16;
;             constexpr bool HOISTK = true;
;             bf16x8 kf[NKS];
;             if (HOISTK) {
; #pragma unroll
;                 for (int s = 0; s < NKS; ++s) kf[s] = *(const bf16x8*)(kb + s * 32);
;             }
;             const unsigned char* vb = a_lds + OFF_V + cur * VBUF + c * VP + (32 * kh + 4 * hi) * 2;
;             bf16x8 vf[8];
;     ...
;             constexpr bool HOISTV = (DK == 128) && (MODE == 2 || MODE == 1);
;             if (HOISTV) A_VREADS(0, 3);
;             if (HOISTK) __builtin_amdgcn_sched_barrier(0);
; #pragma unroll
;             for (int s = 0; s < NKS; ++s) p = __builtin_amdgcn_mfma_f32_32x32x16_bf16(HOISTK ? kf[s] : *(const bf16x8*)(kb + s * 32), qf[s], p, 0, 0, 0);
;             if (HOISTV) { A_VREADS(3, 4); __builtin_amdgcn_sched_barrier(0); }
;             if (MODE == 0) {
;                 const float* ckp = (const float*)(a_lds + OFF_CK + cur * 256) + 32 * kh + 4 * hi;
; #pragma unroll
;                 for (int g = 0; g < 4; ++g) {
;                     const float4 ck = *(const float4*)(ckp + 8 * g);
;                     p[4 * g + 0] = fmaf(p[4 * g + 0], sc2, cq - ck.x); p[4 * g + 1] = fmaf(p[4 * g + 1], sc2, cq - ck.y);
;                     p[4 * g + 2] = fmaf(p[4 * g + 2], sc2, cq - ck.z); p[4 * g + 3] = fmaf(p[4 * g + 3], sc2, cq - ck.w);
;                 }
;                 if (64 * t + 32 * kh + 31 > qw0) {
;                     const int kbase = 64 * t + 32 * kh + 4 * hi;
; #pragma unroll
;                     for (int r = 0; r < 16; ++r) if (kbase + (r & 3) + 8 * (r >> 2) > qrow) p[r] = NEGINF;
;                 }
;             } else if (MODE == 1) {
;                 const float* rb = (const float*)(a_lds + OFF_RB);
;                 if (t <= cw - 3) {
;                     const float bb = rb[256];
; #pragma unroll
.LBB0_959:
	v_cmp_le_i32_e32 vcc, s12, v179
	s_and_saveexec_b64 s[50:51], vcc
	s_cbranch_execz .Lmla_inact
	ds_read_b128 v[82:85], v254
	ds_read_b128 v[186:189], v254 offset:32
	ds_read_b128 v[190:193], v254 offset:64
	ds_read_b128 v[194:197], v254 offset:96
	ds_read_b128 v[208:211], v254 offset:128
	ds_read_b128 v[212:215], v254 offset:160
	ds_read_b128 v[216:219], v254 offset:192
	ds_read_b128 v[220:223], v254 offset:224
	ds_read_b128 v[224:227], v254 offset:256
	ds_read_b128 v[228:231], v254 offset:288
	ds_read_b128 v[232:235], v254 offset:320
	ds_read_b128 v[236:239], v254 offset:352
	v_add_co_u32_e32 v246, vcc, 0xfff80000, v162
	v_lshl_add_u64 v[240:241], v[158:159], 0, v[164:165]
	v_lshl_add_u64 v[242:243], v[158:159], 0, v[168:169]
	v_lshl_add_u64 v[244:245], v[158:159], 0, v[166:167]
	v_addc_co_u32_e32 v247, vcc, -1, v163, vcc
	global_load_dwordx4 v[12:15], v[240:241], off
	global_load_dwordx4 v[4:7], v[242:243], off
	global_load_dwordx4 v[8:11], v[244:245], off
	global_load_dwordx4 v[150:153], v[246:247], off
	global_load_dwordx4 v[146:149], v[162:163], off
	s_waitcnt lgkmcnt(11)
	v_mfma_f32_32x32x16_bf16 v[82:97], v[82:85], v[142:145], 0
	s_mov_b32 s14, 0x41000000
	s_waitcnt lgkmcnt(10)
	v_mfma_f32_32x32x16_bf16 v[82:97], v[186:189], v[138:141], v[82:97]
	s_waitcnt lgkmcnt(9)
	v_mfma_f32_32x32x16_bf16 v[82:97], v[190:193], v[134:137], v[82:97]
	s_waitcnt lgkmcnt(8)
	v_mfma_f32_32x32x16_bf16 v[82:97], v[194:197], v[130:133], v[82:97]
	s_waitcnt lgkmcnt(7)
	v_mfma_f32_32x32x16_bf16 v[82:97], v[208:211], v[126:129], v[82:97]
	s_waitcnt lgkmcnt(6)
	v_mfma_f32_32x32x16_bf16 v[82:97], v[212:215], v[122:125], v[82:97]
	s_waitcnt lgkmcnt(5)
	v_mfma_f32_32x32x16_bf16 v[82:97], v[216:219], v[118:121], v[82:97]
	s_waitcnt lgkmcnt(4)
	v_mfma_f32_32x32x16_bf16 v[82:97], v[220:223], v[114:117], v[82:97]
	s_waitcnt lgkmcnt(3)
	v_mfma_f32_32x32x16_bf16 v[82:97], v[224:227], v[110:113], v[82:97]
	s_waitcnt lgkmcnt(2)
	v_mfma_f32_32x32x16_bf16 v[82:97], v[228:231], v[106:109], v[82:97]
	s_waitcnt lgkmcnt(1)
	v_mfma_f32_32x32x16_bf16 v[82:97], v[232:235], v[102:105], v[82:97]
	s_waitcnt lgkmcnt(0)
	v_mfma_f32_32x32x16_bf16 v[82:97], v[236:239], v[98:101], v[82:97]
	s_mul_i32 s101, s13, 0x4400
	v_add_u32_e32 v250, s101, v174
	v_add_u32_e32 v251, 0xc800, v250
	v_add_u32_e32 v252, 0xd800, v250
	v_add_u32_e32 v253, 0xe800, v250
	v_add_u32_e32 v250, 0xf800, v250
	ds_read2_b64 v[220:223], v251 offset1:2
	ds_read2_b64 v[224:227], v251 offset0:4 offset1:6
	ds_read2_b64 v[186:189], v252 offset0:32 offset1:34
	ds_read2_b64 v[190:193], v252 offset0:36 offset1:38
	ds_read2_b64 v[194:197], v253 offset0:64 offset1:66
	ds_read2_b64 v[208:211], v253 offset0:68 offset1:70
	ds_read2_b64 v[212:215], v250 offset0:96 offset1:98
	ds_read2_b64 v[216:219], v250 offset0:100 offset1:102
	s_nop 1
	v_max_f32_e32 v2, v83, v83
	v_max_f32_e32 v16, v82, v82
	v_max_f32_e32 v2, v16, v2
	v_max3_f32 v2, v2, v84, v85
	v_max3_f32 v2, v2, v86, v87
	v_max3_f32 v2, v2, v88, v89
	v_max3_f32 v2, v2, v90, v91
	v_max3_f32 v2, v2, v92, v93
	v_max3_f32 v2, v2, v94, v95
	v_max3_f32 v2, v2, v96, v97
	v_mul_f32_e32 v2, 0x3dd53b94, v2
	v_mov_b32_e32 v16, v2
	s_nop 1
	v_permlane32_swap_b32_e32 v2, v16
	v_max_f32_e32 v16, v16, v16
	v_max_f32_e32 v2, v2, v2
	v_max_f32_e32 v2, v2, v16
	v_sub_f32_e32 v16, v2, v173
	v_cmp_ge_f32_e32 vcc, s14, v16
	s_cmp_eq_u64 vcc, exec
	s_cbranch_scc1 .LBB0_957
	v_max_f32_e32 v2, v2, v2
	v_max_f32_e32 v16, v173, v173
	v_max_f32_e32 v16, v16, v2
	v_sub_f32_e32 v2, v173, v16
	v_exp_f32_e32 v2, v2
	v_mov_b32_e32 v173, v16
	v_pk_mul_f32 v[80:81], v[80:81], v[2:3] op_sel_hi:[1,0]
	v_pk_mul_f32 v[78:79], v[78:79], v[2:3] op_sel_hi:[1,0]
	v_pk_mul_f32 v[76:77], v[76:77], v[2:3] op_sel_hi:[1,0]
	v_pk_mul_f32 v[74:75], v[74:75], v[2:3] op_sel_hi:[1,0]
	v_pk_mul_f32 v[72:73], v[72:73], v[2:3] op_sel_hi:[1,0]
	v_pk_mul_f32 v[70:71], v[70:71], v[2:3] op_sel_hi:[1,0]
	v_pk_mul_f32 v[68:69], v[68:69], v[2:3] op_sel_hi:[1,0]
	v_pk_mul_f32 v[66:67], v[66:67], v[2:3] op_sel_hi:[1,0]
	v_pk_mul_f32 v[48:49], v[48:49], v[2:3] op_sel_hi:[1,0]
	v_pk_mul_f32 v[46:47], v[46:47], v[2:3] op_sel_hi:[1,0]
	v_pk_mul_f32 v[44:45], v[44:45], v[2:3] op_sel_hi:[1,0]
	v_pk_mul_f32 v[42:43], v[42:43], v[2:3] op_sel_hi:[1,0]
	v_pk_mul_f32 v[40:41], v[40:41], v[2:3] op_sel_hi:[1,0]
	v_pk_mul_f32 v[38:39], v[38:39], v[2:3] op_sel_hi:[1,0]
	v_pk_mul_f32 v[36:37], v[36:37], v[2:3] op_sel_hi:[1,0]
	v_pk_mul_f32 v[34:35], v[34:35], v[2:3] op_sel_hi:[1,0]
	v_pk_mul_f32 v[64:65], v[64:65], v[2:3] op_sel_hi:[1,0]
	v_pk_mul_f32 v[62:63], v[62:63], v[2:3] op_sel_hi:[1,0]
	v_pk_mul_f32 v[60:61], v[60:61], v[2:3] op_sel_hi:[1,0]
	v_pk_mul_f32 v[58:59], v[58:59], v[2:3] op_sel_hi:[1,0]
	v_pk_mul_f32 v[56:57], v[56:57], v[2:3] op_sel_hi:[1,0]
	v_pk_mul_f32 v[54:55], v[54:55], v[2:3] op_sel_hi:[1,0]
	v_pk_mul_f32 v[52:53], v[52:53], v[2:3] op_sel_hi:[1,0]
	v_pk_mul_f32 v[50:51], v[50:51], v[2:3] op_sel_hi:[1,0]
	v_pk_mul_f32 v[32:33], v[32:33], v[2:3] op_sel_hi:[1,0]
	v_pk_mul_f32 v[30:31], v[30:31], v[2:3] op_sel_hi:[1,0]
	v_pk_mul_f32 v[28:29], v[28:29], v[2:3] op_sel_hi:[1,0]
	v_pk_mul_f32 v[26:27], v[26:27], v[2:3] op_sel_hi:[1,0]
	v_pk_mul_f32 v[24:25], v[24:25], v[2:3] op_sel_hi:[1,0]
	v_pk_mul_f32 v[22:23], v[22:23], v[2:3] op_sel_hi:[1,0]
	v_pk_mul_f32 v[20:21], v[20:21], v[2:3] op_sel_hi:[1,0]
	v_pk_mul_f32 v[18:19], v[18:19], v[2:3] op_sel_hi:[1,0]
	v_mul_f32_e32 v171, v171, v2
	s_branch .LBB0_957
